# final f32 output stores (last LN epilogue) write-through sc0 sc1: end-of-kernel L2 flush overlapped
# baseline (speedup 1.0000x reference)
.LBB0_1187:
	s_or_b64 exec, exec, s[6:7]
	v_ashrrev_i32_e32 v141, 31, v140
	v_readlane_b32 s2, v254, 21
	v_lshlrev_b64 v[132:133], 2, v[140:141]
	v_readlane_b32 s3, v254, 22
	s_waitcnt lgkmcnt(0)
	s_barrier
	v_lshl_add_u32 v157, s1, 18, v140
	v_lshl_add_u64 v[0:1], s[2:3], 0, v[132:133]
	v_readlane_b32 s2, v254, 23
	v_readlane_b32 s3, v254, 24
	global_load_dwordx4 v[186:189], v[0:1], off
	v_lshlrev_b32_e32 v2, 10, v144
	v_lshl_add_u64 v[148:149], s[2:3], 0, v[132:133]
	global_load_dwordx4 v[190:193], v[148:149], off
	s_lshl_b32 s2, s0, 9
	s_add_i32 s1, s2, 0
	v_lshl_add_u32 v132, v144, 3, s1
	v_add_u32_e32 v132, 0x2000, v132
	v_lshl_or_b32 v151, s0, 16, v2
	ds_read2_b64 v[144:147], v132 offset1:16
	ds_read2_b64 v[140:143], v132 offset0:32 offset1:48
	ds_read2_b64 v[136:139], v132 offset0:128 offset1:144
	ds_read2_b64 v[132:135], v132 offset0:160 offset1:176
	v_add_u32_e32 v2, v157, v151
	v_or_b32_e32 v152, 0x4000, v151
	v_or_b32_e32 v153, 0x8000, v151
	v_lshl_add_u64 v[168:169], v[2:3], 2, s[40:41]
	v_add_u32_e32 v2, v157, v152
	v_or_b32_e32 v154, 0xc000, v151
	v_lshl_add_u64 v[176:177], v[2:3], 2, s[40:41]
	v_add_u32_e32 v2, v157, v153
	s_waitcnt lgkmcnt(3)
	v_sub_f32_e32 v39, v39, v144
	v_sub_f32_e32 v38, v38, v144
	v_sub_f32_e32 v37, v37, v144
	v_sub_f32_e32 v36, v36, v144
	v_add_u32_e32 v150, 0x20000, v151
	v_lshl_add_u64 v[178:179], v[2:3], 2, s[40:41]
	v_add_u32_e32 v2, v157, v154
	v_sub_f32_e32 v43, v43, v146
	v_sub_f32_e32 v42, v42, v146
	v_sub_f32_e32 v41, v41, v146
	v_sub_f32_e32 v40, v40, v146
	s_waitcnt lgkmcnt(2)
	v_sub_f32_e32 v103, v103, v140
	v_sub_f32_e32 v102, v102, v140
	v_sub_f32_e32 v101, v101, v140
	v_sub_f32_e32 v100, v100, v140
	v_sub_f32_e32 v107, v107, v142
	v_sub_f32_e32 v106, v106, v142
	v_sub_f32_e32 v105, v105, v142
	v_sub_f32_e32 v104, v104, v142
	s_waitcnt lgkmcnt(1)
	v_sub_f32_e32 v131, v131, v136
	v_sub_f32_e32 v130, v130, v136
	v_sub_f32_e32 v129, v129, v136
	v_sub_f32_e32 v128, v128, v136
	v_pk_mul_f32 v[36:37], v[144:145], v[36:37] op_sel:[1,0]
	v_pk_mul_f32 v[38:39], v[144:145], v[38:39] op_sel:[1,0]
	v_add_u32_e32 v155, 0x24000, v151
	v_lshl_add_u64 v[194:195], v[2:3], 2, s[40:41]
	v_add_u32_e32 v2, v157, v150
	v_sub_f32_e32 v199, v123, v138
	v_sub_f32_e32 v198, v122, v138
	v_sub_f32_e32 v201, v121, v138
	v_sub_f32_e32 v200, v120, v138
	v_pk_mul_f32 v[40:41], v[146:147], v[40:41] op_sel:[1,0]
	v_pk_mul_f32 v[42:43], v[146:147], v[42:43] op_sel:[1,0]
	v_pk_mul_f32 v[100:101], v[140:141], v[100:101] op_sel:[1,0]
	v_pk_mul_f32 v[102:103], v[140:141], v[102:103] op_sel:[1,0]
	v_pk_mul_f32 v[104:105], v[142:143], v[104:105] op_sel:[1,0]
	v_pk_mul_f32 v[106:107], v[142:143], v[106:107] op_sel:[1,0]
	v_pk_mul_f32 v[120:121], v[136:137], v[128:129] op_sel:[1,0]
	v_pk_mul_f32 v[122:123], v[136:137], v[130:131] op_sel:[1,0]
	v_lshl_add_u64 v[196:197], v[2:3], 2, s[40:41]
	v_add_u32_e32 v2, v157, v155
	v_sub_f32_e32 v23, v23, v144
	v_sub_f32_e32 v22, v22, v144
	v_sub_f32_e32 v21, v21, v144
	v_sub_f32_e32 v20, v20, v144
	v_sub_f32_e32 v27, v27, v146
	v_sub_f32_e32 v26, v26, v146
	v_sub_f32_e32 v25, v25, v146
	v_sub_f32_e32 v24, v24, v146
	v_pk_mul_f32 v[20:21], v[144:145], v[20:21] op_sel:[1,0]
	v_pk_mul_f32 v[22:23], v[144:145], v[22:23] op_sel:[1,0]
	v_pk_mul_f32 v[24:25], v[146:147], v[24:25] op_sel:[1,0]
	v_pk_mul_f32 v[26:27], v[146:147], v[26:27] op_sel:[1,0]
	v_sub_f32_e32 v15, v15, v144
	v_sub_f32_e32 v14, v14, v144
	v_sub_f32_e32 v13, v13, v144
	v_sub_f32_e32 v12, v12, v144
	v_sub_f32_e32 v17, v17, v146
	v_sub_f32_e32 v16, v16, v146
	v_sub_f32_e32 v19, v19, v146
	v_sub_f32_e32 v18, v18, v146
	v_pk_mul_f32 v[12:13], v[144:145], v[12:13] op_sel:[1,0]
	v_pk_mul_f32 v[14:15], v[144:145], v[14:15] op_sel:[1,0]
	v_pk_mul_f32 v[16:17], v[146:147], v[16:17] op_sel:[1,0]
	s_waitcnt vmcnt(0)
	v_pk_fma_f32 v[38:39], v[38:39], v[188:189], v[192:193]
	v_pk_fma_f32 v[36:37], v[36:37], v[186:187], v[190:191]
	v_pk_fma_f32 v[42:43], v[42:43], v[188:189], v[192:193]
	v_pk_fma_f32 v[40:41], v[40:41], v[186:187], v[190:191]
	v_pk_fma_f32 v[102:103], v[102:103], v[188:189], v[192:193]
	v_pk_fma_f32 v[100:101], v[100:101], v[186:187], v[190:191]
	v_pk_fma_f32 v[106:107], v[106:107], v[188:189], v[192:193]
	v_pk_fma_f32 v[104:105], v[104:105], v[186:187], v[190:191]
	v_pk_fma_f32 v[122:123], v[122:123], v[188:189], v[192:193]
	v_pk_fma_f32 v[120:121], v[120:121], v[186:187], v[190:191]
	global_store_dwordx4 v[168:169], v[36:39], off sc0 sc1
	global_store_dwordx4 v[176:177], v[40:43], off sc0 sc1
	global_store_dwordx4 v[178:179], v[100:103], off sc0 sc1
	global_store_dwordx4 v[194:195], v[104:107], off sc0 sc1
	global_store_dwordx4 v[196:197], v[120:123], off sc0 sc1
	v_pk_mul_f32 v[36:37], v[138:139], v[200:201] op_sel:[1,0]
	v_pk_mul_f32 v[38:39], v[138:139], v[198:199] op_sel:[1,0]
	v_pk_fma_f32 v[36:37], v[186:187], v[36:37], v[190:191]
	v_pk_fma_f32 v[38:39], v[188:189], v[38:39], v[192:193]
	v_lshl_add_u64 v[40:41], v[2:3], 2, s[40:41]
	global_store_dwordx4 v[40:41], v[36:39], off sc0 sc1
	s_waitcnt lgkmcnt(0)
	v_sub_f32_e32 v41, v81, v132
	v_sub_f32_e32 v40, v80, v132
	v_add_u32_e32 v36, 0x28000, v151
	v_sub_f32_e32 v39, v83, v132
	v_sub_f32_e32 v38, v82, v132
	v_add_u32_e32 v2, v157, v36
	v_pk_mul_f32 v[42:43], v[132:133], v[40:41] op_sel:[1,0]
	v_pk_mul_f32 v[38:39], v[132:133], v[38:39] op_sel:[1,0]
	v_add_u32_e32 v37, 0x2c000, v151
	v_pk_fma_f32 v[40:41], v[188:189], v[38:39], v[192:193]
	v_pk_fma_f32 v[38:39], v[186:187], v[42:43], v[190:191]
	v_lshl_add_u64 v[42:43], v[2:3], 2, s[40:41]
	global_store_dwordx4 v[42:43], v[38:41], off sc0 sc1
	v_add_u32_e32 v2, v157, v37
	v_or_b32_e32 v120, 16, v157
	v_sub_f32_e32 v39, v75, v134
	v_sub_f32_e32 v38, v74, v134
	v_sub_f32_e32 v41, v73, v134
	v_sub_f32_e32 v40, v72, v134
	v_pk_mul_f32 v[42:43], v[134:135], v[40:41] op_sel:[1,0]
	v_pk_mul_f32 v[38:39], v[134:135], v[38:39] op_sel:[1,0]
	v_sub_f32_e32 v81, v85, v140
	v_pk_fma_f32 v[40:41], v[188:189], v[38:39], v[192:193]
	v_pk_fma_f32 v[38:39], v[186:187], v[42:43], v[190:191]
	v_lshl_add_u64 v[42:43], v[2:3], 2, s[40:41]
	global_store_dwordx4 v[42:43], v[38:41], off sc0 sc1
	global_load_dwordx4 v[38:41], v[0:1], off offset:64
	s_nop 0
	global_load_dwordx4 v[72:75], v[148:149], off offset:64
	v_add_u32_e32 v2, v120, v151
	v_lshl_add_u64 v[100:101], v[2:3], 2, s[40:41]
	v_add_u32_e32 v2, v120, v152
	v_sub_f32_e32 v43, v87, v140
	v_sub_f32_e32 v42, v86, v140
	v_sub_f32_e32 v80, v84, v140
	v_sub_f32_e32 v83, v91, v142
	v_sub_f32_e32 v82, v90, v142
	v_sub_f32_e32 v85, v89, v142
	v_sub_f32_e32 v84, v88, v142
	v_lshl_add_u64 v[102:103], v[2:3], 2, s[40:41]
	v_add_u32_e32 v2, v120, v153
	v_sub_f32_e32 v89, v127, v136
	v_sub_f32_e32 v88, v126, v136
	v_sub_f32_e32 v91, v125, v136
	v_sub_f32_e32 v90, v124, v136
	v_pk_mul_f32 v[80:81], v[140:141], v[80:81] op_sel:[1,0]
	v_pk_mul_f32 v[42:43], v[140:141], v[42:43] op_sel:[1,0]
	v_pk_mul_f32 v[84:85], v[142:143], v[84:85] op_sel:[1,0]
	v_pk_mul_f32 v[86:87], v[142:143], v[82:83] op_sel:[1,0]
	v_lshl_add_u64 v[104:105], v[2:3], 2, s[40:41]
	v_add_u32_e32 v2, v120, v154
	v_lshl_add_u64 v[106:107], v[2:3], 2, s[40:41]
	v_add_u32_e32 v2, v120, v150
	v_pk_mul_f32 v[18:19], v[146:147], v[18:19] op_sel:[1,0]
	v_sub_f32_e32 v5, v5, v144
	v_sub_f32_e32 v4, v4, v144
	v_sub_f32_e32 v9, v9, v146
	v_sub_f32_e32 v8, v8, v146
	v_pk_mul_f32 v[4:5], v[144:145], v[4:5] op_sel:[1,0]
	v_pk_mul_f32 v[8:9], v[146:147], v[8:9] op_sel:[1,0]
	s_waitcnt vmcnt(0)
	v_pk_fma_f32 v[22:23], v[22:23], v[40:41], v[74:75]
	v_pk_fma_f32 v[20:21], v[20:21], v[38:39], v[72:73]
	v_pk_fma_f32 v[26:27], v[26:27], v[40:41], v[74:75]
	v_pk_fma_f32 v[24:25], v[24:25], v[38:39], v[72:73]
	v_pk_fma_f32 v[82:83], v[42:43], v[40:41], v[74:75]
	v_pk_fma_f32 v[80:81], v[80:81], v[38:39], v[72:73]
	v_pk_fma_f32 v[86:87], v[86:87], v[40:41], v[74:75]
	v_pk_fma_f32 v[84:85], v[84:85], v[38:39], v[72:73]
	global_store_dwordx4 v[100:101], v[20:23], off sc0 sc1
	global_store_dwordx4 v[102:103], v[24:27], off sc0 sc1
	global_store_dwordx4 v[104:105], v[80:83], off sc0 sc1
	global_store_dwordx4 v[106:107], v[84:87], off sc0 sc1
	v_pk_mul_f32 v[20:21], v[136:137], v[90:91] op_sel:[1,0]
	v_pk_mul_f32 v[22:23], v[136:137], v[88:89] op_sel:[1,0]
	v_pk_fma_f32 v[20:21], v[20:21], v[38:39], v[72:73]
	v_pk_fma_f32 v[22:23], v[22:23], v[40:41], v[74:75]
	v_lshl_add_u64 v[24:25], v[2:3], 2, s[40:41]
	global_store_dwordx4 v[24:25], v[20:23], off sc0 sc1
	v_add_u32_e32 v2, v120, v155
	v_sub_f32_e32 v43, v71, v142
	v_sub_f32_e32 v21, v119, v138
	v_sub_f32_e32 v20, v118, v138
	v_sub_f32_e32 v23, v117, v138
	v_sub_f32_e32 v22, v116, v138
	v_pk_mul_f32 v[24:25], v[138:139], v[22:23] op_sel:[1,0]
	v_pk_mul_f32 v[20:21], v[138:139], v[20:21] op_sel:[1,0]
	v_sub_f32_e32 v42, v70, v142
	v_pk_fma_f32 v[22:23], v[20:21], v[40:41], v[74:75]
	v_pk_fma_f32 v[20:21], v[24:25], v[38:39], v[72:73]
	v_lshl_add_u64 v[24:25], v[2:3], 2, s[40:41]
	global_store_dwordx4 v[24:25], v[20:23], off sc0 sc1
	v_add_u32_e32 v2, v120, v36
	v_pk_mul_f32 v[42:43], v[142:143], v[42:43] op_sel:[1,0]
	v_sub_f32_e32 v21, v79, v132
	v_sub_f32_e32 v20, v78, v132
	v_sub_f32_e32 v23, v77, v132
	v_sub_f32_e32 v22, v76, v132
	v_pk_mul_f32 v[24:25], v[132:133], v[22:23] op_sel:[1,0]
	v_pk_mul_f32 v[20:21], v[132:133], v[20:21] op_sel:[1,0]
	s_nop 0
	v_pk_fma_f32 v[22:23], v[20:21], v[40:41], v[74:75]
	v_pk_fma_f32 v[20:21], v[24:25], v[38:39], v[72:73]
	v_lshl_add_u64 v[24:25], v[2:3], 2, s[40:41]
	global_store_dwordx4 v[24:25], v[20:23], off sc0 sc1
	v_add_u32_e32 v2, v120, v37
	s_nop 0
	v_sub_f32_e32 v21, v63, v134
	v_sub_f32_e32 v20, v62, v134
	v_sub_f32_e32 v23, v61, v134
	v_sub_f32_e32 v22, v60, v134
	v_pk_mul_f32 v[24:25], v[134:135], v[22:23] op_sel:[1,0]
	v_pk_mul_f32 v[20:21], v[134:135], v[20:21] op_sel:[1,0]
	v_sub_f32_e32 v61, v69, v142
	v_pk_fma_f32 v[22:23], v[20:21], v[40:41], v[74:75]
	v_pk_fma_f32 v[20:21], v[24:25], v[38:39], v[72:73]
	v_lshl_add_u64 v[24:25], v[2:3], 2, s[40:41]
	global_store_dwordx4 v[24:25], v[20:23], off sc0 sc1
	global_load_dwordx4 v[20:23], v[0:1], off offset:512
	s_nop 0
	global_load_dwordx4 v[24:27], v[148:149], off offset:512
	v_or_b32_e32 v72, 0x80, v157
	v_add_u32_e32 v2, v72, v151
	v_sub_f32_e32 v41, v65, v140
	v_sub_f32_e32 v40, v64, v140
	v_lshl_add_u64 v[64:65], v[2:3], 2, s[40:41]
	v_add_u32_e32 v2, v72, v152
	v_sub_f32_e32 v39, v67, v140
	v_sub_f32_e32 v38, v66, v140
	v_sub_f32_e32 v60, v68, v142
	v_lshl_add_u64 v[66:67], v[2:3], 2, s[40:41]
	v_add_u32_e32 v2, v72, v153
	v_pk_mul_f32 v[62:63], v[140:141], v[40:41] op_sel:[1,0]
	v_pk_mul_f32 v[38:39], v[140:141], v[38:39] op_sel:[1,0]
	v_pk_mul_f32 v[60:61], v[142:143], v[60:61] op_sel:[1,0]
	v_lshl_add_u64 v[68:69], v[2:3], 2, s[40:41]
	v_add_u32_e32 v2, v72, v154
	s_waitcnt vmcnt(0)
	v_pk_fma_f32 v[14:15], v[14:15], v[22:23], v[26:27]
	v_pk_fma_f32 v[12:13], v[12:13], v[20:21], v[24:25]
	v_pk_fma_f32 v[16:17], v[16:17], v[20:21], v[24:25]
	v_pk_fma_f32 v[18:19], v[18:19], v[22:23], v[26:27]
	v_pk_fma_f32 v[40:41], v[38:39], v[22:23], v[26:27]
	v_pk_fma_f32 v[38:39], v[62:63], v[20:21], v[24:25]
	global_store_dwordx4 v[64:65], v[12:15], off sc0 sc1
	global_store_dwordx4 v[66:67], v[16:19], off sc0 sc1
	global_store_dwordx4 v[68:69], v[38:41], off sc0 sc1
	v_pk_fma_f32 v[14:15], v[42:43], v[22:23], v[26:27]
	v_pk_fma_f32 v[12:13], v[60:61], v[20:21], v[24:25]
	v_lshl_add_u64 v[16:17], v[2:3], 2, s[40:41]
	global_store_dwordx4 v[16:17], v[12:15], off sc0 sc1
	v_add_u32_e32 v2, v72, v150
	v_or_b32_e32 v38, 0x90, v157
	v_sub_f32_e32 v13, v111, v136
	v_sub_f32_e32 v12, v110, v136
	v_sub_f32_e32 v15, v109, v136
	v_sub_f32_e32 v14, v108, v136
	v_pk_mul_f32 v[16:17], v[136:137], v[14:15] op_sel:[1,0]
	v_pk_mul_f32 v[12:13], v[136:137], v[12:13] op_sel:[1,0]
	s_nop 0
	v_pk_fma_f32 v[14:15], v[12:13], v[22:23], v[26:27]
	v_pk_fma_f32 v[12:13], v[16:17], v[20:21], v[24:25]
	v_lshl_add_u64 v[16:17], v[2:3], 2, s[40:41]
	global_store_dwordx4 v[16:17], v[12:15], off sc0 sc1
	v_add_u32_e32 v2, v72, v155
	s_nop 0
	v_sub_f32_e32 v13, v115, v138
	v_sub_f32_e32 v12, v114, v138
	v_sub_f32_e32 v15, v113, v138
	v_sub_f32_e32 v14, v112, v138
	v_pk_mul_f32 v[16:17], v[138:139], v[14:15] op_sel:[1,0]
	v_pk_mul_f32 v[12:13], v[138:139], v[12:13] op_sel:[1,0]
	s_nop 0
	v_pk_fma_f32 v[14:15], v[12:13], v[22:23], v[26:27]
	v_pk_fma_f32 v[12:13], v[16:17], v[20:21], v[24:25]
	v_lshl_add_u64 v[16:17], v[2:3], 2, s[40:41]
	global_store_dwordx4 v[16:17], v[12:15], off sc0 sc1
	v_add_u32_e32 v2, v72, v36
	s_nop 0
	v_sub_f32_e32 v13, v59, v132
	v_sub_f32_e32 v12, v58, v132
	v_sub_f32_e32 v15, v57, v132
	v_sub_f32_e32 v14, v56, v132
	v_pk_mul_f32 v[16:17], v[132:133], v[14:15] op_sel:[1,0]
	v_pk_mul_f32 v[12:13], v[132:133], v[12:13] op_sel:[1,0]
	s_nop 0
	v_pk_fma_f32 v[14:15], v[12:13], v[22:23], v[26:27]
	v_pk_fma_f32 v[12:13], v[16:17], v[20:21], v[24:25]
	v_lshl_add_u64 v[16:17], v[2:3], 2, s[40:41]
	global_store_dwordx4 v[16:17], v[12:15], off sc0 sc1
	v_add_u32_e32 v2, v72, v37
	s_nop 0
	v_sub_f32_e32 v13, v51, v134
	v_sub_f32_e32 v12, v50, v134
	v_sub_f32_e32 v15, v49, v134
	v_sub_f32_e32 v14, v48, v134
	v_pk_mul_f32 v[16:17], v[134:135], v[14:15] op_sel:[1,0]
	v_pk_mul_f32 v[12:13], v[134:135], v[12:13] op_sel:[1,0]
	s_nop 0
	v_pk_fma_f32 v[14:15], v[12:13], v[22:23], v[26:27]
	v_pk_fma_f32 v[12:13], v[16:17], v[20:21], v[24:25]
	v_lshl_add_u64 v[16:17], v[2:3], 2, s[40:41]
	global_store_dwordx4 v[16:17], v[12:15], off sc0 sc1
	global_load_dwordx4 v[12:15], v[0:1], off offset:576
	s_nop 0
	global_load_dwordx4 v[16:19], v[148:149], off offset:576
	v_add_u32_e32 v2, v38, v151
	v_sub_f32_e32 v1, v7, v144
	v_sub_f32_e32 v0, v6, v144
	v_sub_f32_e32 v7, v11, v146
	v_sub_f32_e32 v6, v10, v146
	v_sub_f32_e32 v11, v35, v140
	v_sub_f32_e32 v10, v34, v140
	v_sub_f32_e32 v21, v33, v140
	v_sub_f32_e32 v20, v32, v140
	v_lshl_add_u64 v[26:27], v[2:3], 2, s[40:41]
	v_add_u32_e32 v2, v38, v152
	v_pk_mul_f32 v[0:1], v[144:145], v[0:1] op_sel:[1,0]
	v_pk_mul_f32 v[22:23], v[146:147], v[6:7] op_sel:[1,0]
	v_pk_mul_f32 v[20:21], v[140:141], v[20:21] op_sel:[1,0]
	v_pk_mul_f32 v[24:25], v[140:141], v[10:11] op_sel:[1,0]
	v_lshl_add_u64 v[32:33], v[2:3], 2, s[40:41]
	v_add_u32_e32 v2, v38, v153
	s_waitcnt vmcnt(0)
	v_pk_fma_f32 v[6:7], v[0:1], v[14:15], v[18:19]
	v_pk_fma_f32 v[4:5], v[4:5], v[12:13], v[16:17]
	v_pk_fma_f32 v[10:11], v[22:23], v[14:15], v[18:19]
	v_pk_fma_f32 v[22:23], v[24:25], v[14:15], v[18:19]
	v_pk_fma_f32 v[20:21], v[20:21], v[12:13], v[16:17]
	v_lshl_add_u64 v[0:1], v[2:3], 2, s[40:41]
	v_pk_fma_f32 v[8:9], v[8:9], v[12:13], v[16:17]
	global_store_dwordx4 v[26:27], v[4:7], off sc0 sc1
	global_store_dwordx4 v[32:33], v[8:11], off sc0 sc1
	global_store_dwordx4 v[0:1], v[20:23], off sc0 sc1
	v_sub_f32_e32 v1, v31, v142
	v_sub_f32_e32 v0, v30, v142
	v_sub_f32_e32 v5, v29, v142
	v_sub_f32_e32 v4, v28, v142
	v_add_u32_e32 v2, v38, v154
	v_pk_mul_f32 v[4:5], v[142:143], v[4:5] op_sel:[1,0]
	v_pk_mul_f32 v[0:1], v[142:143], v[0:1] op_sel:[1,0]
	v_pk_fma_f32 v[4:5], v[4:5], v[12:13], v[16:17]
	v_pk_fma_f32 v[6:7], v[0:1], v[14:15], v[18:19]
	v_lshl_add_u64 v[0:1], v[2:3], 2, s[40:41]
	global_store_dwordx4 v[0:1], v[4:7], off sc0 sc1
	v_sub_f32_e32 v1, v95, v136
	v_sub_f32_e32 v0, v94, v136
	v_sub_f32_e32 v5, v93, v136
	v_sub_f32_e32 v4, v92, v136
	v_add_u32_e32 v2, v38, v150
	v_pk_mul_f32 v[4:5], v[136:137], v[4:5] op_sel:[1,0]
	v_pk_mul_f32 v[0:1], v[136:137], v[0:1] op_sel:[1,0]
	v_pk_fma_f32 v[4:5], v[4:5], v[12:13], v[16:17]
	v_pk_fma_f32 v[6:7], v[0:1], v[14:15], v[18:19]
	v_lshl_add_u64 v[0:1], v[2:3], 2, s[40:41]
	global_store_dwordx4 v[0:1], v[4:7], off sc0 sc1
	v_sub_f32_e32 v1, v99, v138
	v_sub_f32_e32 v0, v98, v138
	v_sub_f32_e32 v5, v97, v138
	v_sub_f32_e32 v4, v96, v138
	v_add_u32_e32 v2, v38, v155
	v_pk_mul_f32 v[4:5], v[138:139], v[4:5] op_sel:[1,0]
	v_pk_mul_f32 v[0:1], v[138:139], v[0:1] op_sel:[1,0]
	v_pk_fma_f32 v[4:5], v[4:5], v[12:13], v[16:17]
	v_pk_fma_f32 v[6:7], v[0:1], v[14:15], v[18:19]
	v_lshl_add_u64 v[0:1], v[2:3], 2, s[40:41]
	global_store_dwordx4 v[0:1], v[4:7], off sc0 sc1
	v_sub_f32_e32 v1, v55, v132
	v_sub_f32_e32 v0, v54, v132
	v_sub_f32_e32 v5, v53, v132
	v_sub_f32_e32 v4, v52, v132
	v_add_u32_e32 v2, v38, v36
	v_pk_mul_f32 v[4:5], v[132:133], v[4:5] op_sel:[1,0]
	v_pk_mul_f32 v[0:1], v[132:133], v[0:1] op_sel:[1,0]
	v_pk_fma_f32 v[4:5], v[4:5], v[12:13], v[16:17]
	v_pk_fma_f32 v[6:7], v[0:1], v[14:15], v[18:19]
	v_lshl_add_u64 v[0:1], v[2:3], 2, s[40:41]
	global_store_dwordx4 v[0:1], v[4:7], off sc0 sc1
	v_sub_f32_e32 v1, v47, v134
	v_sub_f32_e32 v0, v46, v134
	v_sub_f32_e32 v5, v45, v134
	v_sub_f32_e32 v4, v44, v134
	v_add_u32_e32 v2, v38, v37
	v_pk_mul_f32 v[4:5], v[134:135], v[4:5] op_sel:[1,0]
	v_pk_mul_f32 v[0:1], v[134:135], v[0:1] op_sel:[1,0]
	v_pk_fma_f32 v[4:5], v[4:5], v[12:13], v[16:17]
	v_pk_fma_f32 v[6:7], v[0:1], v[14:15], v[18:19]
	v_lshl_add_u64 v[0:1], v[2:3], 2, s[40:41]
	global_store_dwordx4 v[0:1], v[4:7], off sc0 sc1
